# phase A norm: adaLN table fill loads batched (6 loads in flight instead of 6 serialized round trips), on top of v51
# baseline (speedup 1.0000x reference)
.LBB0_276:
	s_mul_i32 s0, s92, 0x7800
	s_mov_b32 s1, s67
	v_writelane_b32 v255, s0, 2
	s_nop 1
	v_writelane_b32 v255, s1, 3
	s_lshl_b32 s0, s92, 10
	s_mov_b32 s1, s67
	v_writelane_b32 v255, s0, 4
	s_nop 1
	v_writelane_b32 v255, s1, 5
	s_movk_i32 s0, 0xb00
	v_cmp_gt_i32_e32 vcc, s0, v10
	s_and_saveexec_b64 s[0:1], vcc
	s_cbranch_execz .LBB0_287
	v_readlane_b32 s8, v255, 2
	v_readlane_b32 s9, v255, 3
	s_lshl_b64 s[8:9], s[8:9], 2
	s_waitcnt lgkmcnt(0)
	s_add_u32 s8, s2, s8
	s_addc_u32 s9, s3, s9
	v_readlane_b32 s12, v255, 4
	s_add_u32 s8, s8, 0x100000
	v_readlane_b32 s13, v255, 5
	s_addc_u32 s9, s9, 0
	s_lshl_b64 s[12:13], s[12:13], 2
	s_add_u32 s10, s10, s12
	v_and_b32_e32 v0, 0xff, v10
	s_addc_u32 s11, s11, s13
	v_lshlrev_b32_e32 v64, 4, v0
	v_lshl_add_u64 v[4:5], s[8:9], 0, v[64:65]
	v_lshl_add_u64 v[6:7], s[10:11], 0, v[64:65]
	v_lshl_add_u32 v11, v10, 4, 0
	s_mov_b64 s[10:11], 0
	v_lshlrev_b32_e32 v8, 4, v0
	v_mov_b32_e32 v12, v10
	s_movk_i32 s12, 0xff
	v_cmp_lt_u32_e32 vcc, s12, v10
	s_mov_b64 s[14:15], vcc
	v_mov_b32_e32 v12, 0x6000
	v_cndmask_b32_e32 v12, 0, v12, vcc
	v_mov_b32_e32 v13, 0
	v_cndmask_b32_e32 v0, v6, v4, vcc
	v_cndmask_b32_e32 v1, v7, v5, vcc
	global_load_dwordx4 v[16:19], v[0:1], off
	v_lshl_add_u64 v[2:3], v[4:5], 0, v[12:13]
	s_mov_b32 s12, 0x6000
	s_mov_b32 s13, 0
	v_lshl_add_u64 v[0:1], v[2:3], 0, s[12:13]
	global_load_dwordx4 v[20:23], v[0:1], off
	s_mov_b32 s12, 0x12000
	s_mov_b32 s13, 0
	v_lshl_add_u64 v[0:1], v[2:3], 0, s[12:13]
	global_load_dwordx4 v[24:27], v[0:1], off
	s_mov_b32 s12, 0x1000
	s_mov_b32 s13, 0
	v_lshl_add_u64 v[0:1], v[2:3], 0, s[12:13]
	global_load_dwordx4 v[28:31], v[0:1], off
	s_mov_b32 s12, 0xd000
	s_mov_b32 s13, 0
	v_lshl_add_u64 v[0:1], v[2:3], 0, s[12:13]
	global_load_dwordx4 v[32:35], v[0:1], off
	s_andn2_b64 s[12:13], exec, s[14:15]
	s_and_saveexec_b64 s[10:11], s[12:13]
	s_mov_b32 s12, 0x19000
	s_mov_b32 s13, 0
	v_lshl_add_u64 v[0:1], v[4:5], 0, s[12:13]
	global_load_dwordx4 v[36:39], v[0:1], off
	s_mov_b64 exec, s[10:11]
	s_waitcnt vmcnt(5)
	ds_write_b128 v11, v[16:19]
	s_waitcnt vmcnt(4)
	ds_write_b128 v11, v[20:23] offset:8192
	s_waitcnt vmcnt(3)
	ds_write_b128 v11, v[24:27] offset:16384
	s_waitcnt vmcnt(2)
	v_pk_add_f32 v[30:31], v[30:31], 1.0 op_sel_hi:[1,0]
	v_pk_add_f32 v[28:29], v[28:29], 1.0 op_sel_hi:[1,0]
	ds_write_b128 v11, v[28:31] offset:24576
	s_waitcnt vmcnt(1)
	v_pk_add_f32 v[34:35], v[34:35], 1.0 op_sel_hi:[1,0]
	v_pk_add_f32 v[32:33], v[32:33], 1.0 op_sel_hi:[1,0]
	ds_write_b128 v11, v[32:35] offset:32768
	s_waitcnt vmcnt(0)
	s_andn2_b64 s[12:13], exec, s[14:15]
	s_and_saveexec_b64 s[10:11], s[12:13]
	v_pk_add_f32 v[38:39], v[38:39], 1.0 op_sel_hi:[1,0]
	v_pk_add_f32 v[36:37], v[36:37], 1.0 op_sel_hi:[1,0]
	ds_write_b128 v11, v[36:39] offset:40960
	s_mov_b64 exec, s[10:11]
